# mixers: attention row max/sum across lane^16/32 via permlane16/32_swap, mLSTM 16-lane sums via DPP and batched normaliser reads instead of ds_bpermute round trips (bit-identical)
# speedup vs baseline: 1.0307x; 1.0157x over previous
; __device__ __forceinline__ void attn_unit(int u, int l, const bf16_t* proj, const float* a_lambda, const float* a_norm_w, bf16_t* ha, LAS unsigned char* lds) {
;     ...
;             float mx = -1e30f;
; #pragma unroll
;             for (int it = 0; it < 4; ++it) mx = fmaxf(mx, fmaxf(fmaxf(s[it][0], s[it][1]), fmaxf(s[it][2], s[it][3])));
;             mx = fmaxf(mx, __shfl_xor(mx, 16)); mx = fmaxf(mx, __shfl_xor(mx, 32));
;             const float mnew = (mx > mrow[n] + 8.0f) ? mx : mrow[n];
;             float ps = 0.f;
; #pragma unroll
;             for (int it = 0; it < 4; ++it)
; #pragma unroll
;                 for (int r = 0; r < 4; ++r) { s[it][r] = __builtin_amdgcn_exp2f(s[it][r] - mnew); ps += s[it][r]; }
;             ps += __shfl_xor(ps, 16); ps += __shfl_xor(ps, 32);
;             if (__builtin_amdgcn_ballot_w64(mnew != mrow[n]) != 0ull) {
;                 const float alpha = __builtin_amdgcn_exp2f(mrow[n] - mnew);
;                 lrow[n] = lrow[n] * alpha;
; #pragma unroll
;                 for (int e = 0; e < 8; ++e) O[n][e] = O[n][e] * alpha;
;             }
.LBB0_289:
	v_max_f32_e32 v2, v115, v115
	v_max_f32_e32 v3, v114, v114
	v_max_f32_e32 v2, v3, v2
	v_max_f32_e32 v3, v111, v111
	v_max_f32_e32 v141, v110, v110
	v_max_f32_e32 v3, v141, v3
	v_max3_f32 v2, v112, v113, v2
	v_max3_f32 v3, v108, v109, v3
	v_max3_f32 v2, v2, s93, v3
	v_max_f32_e32 v3, v107, v107
	v_max_f32_e32 v141, v106, v106
	v_max_f32_e32 v3, v141, v3
	v_max_f32_e32 v141, v103, v103
	v_max_f32_e32 v142, v102, v102
	v_max_f32_e32 v141, v142, v141
	v_max3_f32 v3, v104, v105, v3
	v_max3_f32 v141, v100, v101, v141
	v_max3_f32 v2, v2, v3, v141
	v_mov_b32_e32 v3, v2
	s_nop 1
	v_permlane16_swap_b32 v3, v2
	s_waitcnt lgkmcnt(0)
	v_max_f32_e32 v3, v3, v3
	v_max_f32_e32 v2, v2, v3
	v_mov_b32_e32 v3, v2
	s_nop 1
	v_permlane32_swap_b32 v3, v2
	s_waitcnt lgkmcnt(0)
	v_max_f32_e32 v3, v3, v3
	v_max_f32_e32 v2, v2, v3
	v_add_f32_e32 v3, 0x41000000, v174
	v_cmp_gt_f32_e32 vcc, v2, v3
	s_nop 1
	v_cndmask_b32_e32 v2, v174, v2, vcc
	v_sub_f32_e32 v3, v112, v2
	v_exp_f32_e32 v151, v3
	v_sub_f32_e32 v3, v113, v2
	v_exp_f32_e32 v152, v3
	v_sub_f32_e32 v3, v114, v2
	v_exp_f32_e32 v153, v3
	v_sub_f32_e32 v3, v115, v2
	v_exp_f32_e32 v154, v3
	v_sub_f32_e32 v108, v108, v2
	v_add_f32_e32 v3, 0, v151
	v_exp_f32_e32 v155, v108
	v_sub_f32_e32 v108, v109, v2
	v_add_f32_e32 v3, v152, v3
	v_exp_f32_e32 v156, v108
	v_sub_f32_e32 v108, v110, v2
	v_add_f32_e32 v3, v153, v3
	v_exp_f32_e32 v157, v108
	v_sub_f32_e32 v108, v111, v2
	v_add_f32_e32 v3, v154, v3
	v_exp_f32_e32 v158, v108
	v_sub_f32_e32 v104, v104, v2
	v_add_f32_e32 v3, v155, v3
	v_exp_f32_e32 v142, v104
	v_sub_f32_e32 v104, v105, v2
	v_add_f32_e32 v3, v156, v3
	v_exp_f32_e32 v143, v104
	v_sub_f32_e32 v104, v106, v2
	v_add_f32_e32 v3, v157, v3
	v_exp_f32_e32 v144, v104
	v_sub_f32_e32 v104, v107, v2
	v_add_f32_e32 v3, v158, v3
	v_exp_f32_e32 v145, v104
	v_sub_f32_e32 v100, v100, v2
	v_add_f32_e32 v3, v142, v3
	v_exp_f32_e32 v146, v100
	v_sub_f32_e32 v100, v101, v2
	v_add_f32_e32 v3, v143, v3
	v_exp_f32_e32 v147, v100
	v_sub_f32_e32 v100, v102, v2
	v_add_f32_e32 v3, v144, v3
	v_exp_f32_e32 v148, v100
	v_sub_f32_e32 v100, v103, v2
	v_add_f32_e32 v3, v145, v3
	v_exp_f32_e32 v149, v100
	v_add_f32_e32 v3, v146, v3
	v_add_f32_e32 v3, v147, v3
	v_add_f32_e32 v3, v148, v3
	v_add_f32_e32 v3, v149, v3
	v_mov_b32_e32 v100, v3
	s_nop 1
	v_permlane16_swap_b32 v100, v3
	v_cmp_neq_f32_e32 vcc, v2, v174
	s_waitcnt lgkmcnt(0)
	v_add_f32_e32 v3, v3, v100
	v_mov_b32_e32 v141, v3
	s_nop 1
	v_permlane32_swap_b32 v141, v3
	s_cbranch_vccz .LBB0_291
	v_sub_f32_e32 v100, v174, v2
	v_exp_f32_e32 v100, v100
	s_nop 0
	v_mul_f32_e32 v129, v129, v100
	v_pk_mul_f32 v[66:67], v[66:67], v[100:101] op_sel_hi:[1,0]
	v_pk_mul_f32 v[64:65], v[64:65], v[100:101] op_sel_hi:[1,0]
	v_pk_mul_f32 v[62:63], v[62:63], v[100:101] op_sel_hi:[1,0]
	v_pk_mul_f32 v[60:61], v[60:61], v[100:101] op_sel_hi:[1,0]
	v_pk_mul_f32 v[50:51], v[50:51], v[100:101] op_sel_hi:[1,0]
	v_pk_mul_f32 v[48:49], v[48:49], v[100:101] op_sel_hi:[1,0]
	v_pk_mul_f32 v[42:43], v[42:43], v[100:101] op_sel_hi:[1,0]
	v_pk_mul_f32 v[40:41], v[40:41], v[100:101] op_sel_hi:[1,0]
	v_pk_mul_f32 v[34:35], v[34:35], v[100:101] op_sel_hi:[1,0]
	v_pk_mul_f32 v[32:33], v[32:33], v[100:101] op_sel_hi:[1,0]
	v_pk_mul_f32 v[26:27], v[26:27], v[100:101] op_sel_hi:[1,0]
	v_pk_mul_f32 v[24:25], v[24:25], v[100:101] op_sel_hi:[1,0]
	v_pk_mul_f32 v[14:15], v[14:15], v[100:101] op_sel_hi:[1,0]
	v_pk_mul_f32 v[12:13], v[12:13], v[100:101] op_sel_hi:[1,0]
	v_pk_mul_f32 v[10:11], v[10:11], v[100:101] op_sel_hi:[1,0]
	v_pk_mul_f32 v[8:9], v[8:9], v[100:101] op_sel_hi:[1,0]

; __device__ __forceinline__ void attn_unit(int u, int l, const bf16_t* proj, const float* a_lambda, const float* a_norm_w, bf16_t* ha, LAS unsigned char* lds) {
;     ...
;             float mx = -1e30f;
; #pragma unroll
;             for (int it = 0; it < 4; ++it) mx = fmaxf(mx, fmaxf(fmaxf(s[it][0], s[it][1]), fmaxf(s[it][2], s[it][3])));
;             mx = fmaxf(mx, __shfl_xor(mx, 16)); mx = fmaxf(mx, __shfl_xor(mx, 32));
;             const float mnew = (mx > mrow[n] + 8.0f) ? mx : mrow[n];
;             float ps = 0.f;
; #pragma unroll
;             for (int it = 0; it < 4; ++it)
; #pragma unroll
;                 for (int r = 0; r < 4; ++r) { s[it][r] = __builtin_amdgcn_exp2f(s[it][r] - mnew); ps += s[it][r]; }
;             ps += __shfl_xor(ps, 16); ps += __shfl_xor(ps, 32);
;             if (__builtin_amdgcn_ballot_w64(mnew != mrow[n]) != 0ull) {
;                 const float alpha = __builtin_amdgcn_exp2f(mrow[n] - mnew);
;                 lrow[n] = lrow[n] * alpha;
; #pragma unroll
;                 for (int e = 0; e < 8; ++e) O[n][e] = O[n][e] * alpha;
;             }
.LBB0_293:
	v_max_f32_e32 v1, v103, v103
	v_max_f32_e32 v159, v102, v102
	v_max_f32_e32 v1, v159, v1
	v_max_f32_e32 v159, v107, v107
	v_max_f32_e32 v160, v106, v106
	v_max_f32_e32 v159, v160, v159
	v_max3_f32 v1, v100, v101, v1
	v_max3_f32 v159, v104, v105, v159
	v_max3_f32 v1, v1, s93, v159
	v_max_f32_e32 v159, v111, v111
	v_max_f32_e32 v160, v110, v110
	v_max_f32_e32 v159, v160, v159
	v_max_f32_e32 v160, v115, v115
	v_max_f32_e32 v161, v114, v114
	v_max_f32_e32 v160, v161, v160
	v_max3_f32 v159, v108, v109, v159
	v_max3_f32 v160, v112, v113, v160
	v_max3_f32 v1, v1, v159, v160
	v_mov_b32_e32 v159, v1
	s_nop 1
	v_permlane16_swap_b32 v159, v1
	s_waitcnt lgkmcnt(0)
	v_max_f32_e32 v159, v159, v159
	v_max_f32_e32 v1, v1, v159
	v_mov_b32_e32 v159, v1
	s_nop 1
	v_permlane32_swap_b32 v159, v1
	s_waitcnt lgkmcnt(0)
	v_max_f32_e32 v159, v159, v159
	v_max_f32_e32 v1, v1, v159
	v_add_f32_e32 v159, 0x41000000, v150
	v_cmp_gt_f32_e32 vcc, v1, v159
	s_nop 1
	v_cndmask_b32_e32 v1, v150, v1, vcc
	v_sub_f32_e32 v100, v100, v1
	v_exp_f32_e32 v159, v100
	v_sub_f32_e32 v100, v101, v1
	v_exp_f32_e32 v160, v100
	v_sub_f32_e32 v100, v102, v1
	v_exp_f32_e32 v161, v100
	v_sub_f32_e32 v100, v103, v1
	v_exp_f32_e32 v162, v100
	v_sub_f32_e32 v101, v104, v1
	v_add_f32_e32 v100, 0, v159
	v_exp_f32_e32 v163, v101
	v_sub_f32_e32 v101, v105, v1
	v_add_f32_e32 v100, v160, v100
	v_exp_f32_e32 v164, v101
	v_sub_f32_e32 v101, v106, v1
	v_add_f32_e32 v100, v161, v100
	v_exp_f32_e32 v165, v101
	v_sub_f32_e32 v101, v107, v1
	v_add_f32_e32 v100, v162, v100
	v_exp_f32_e32 v166, v101
	v_sub_f32_e32 v101, v108, v1
	v_add_f32_e32 v100, v163, v100
	v_exp_f32_e32 v102, v101
	v_sub_f32_e32 v101, v109, v1
	v_add_f32_e32 v100, v164, v100
	v_exp_f32_e32 v103, v101
	v_sub_f32_e32 v101, v110, v1
	v_add_f32_e32 v100, v165, v100
	v_exp_f32_e32 v104, v101
	v_sub_f32_e32 v101, v111, v1
	v_add_f32_e32 v100, v166, v100
	v_exp_f32_e32 v105, v101
	v_sub_f32_e32 v101, v112, v1
	v_add_f32_e32 v100, v102, v100
	v_exp_f32_e32 v106, v101
	v_sub_f32_e32 v101, v113, v1
	v_add_f32_e32 v100, v103, v100
	v_exp_f32_e32 v107, v101
	v_sub_f32_e32 v101, v114, v1
	v_add_f32_e32 v100, v104, v100
	v_exp_f32_e32 v108, v101
	v_sub_f32_e32 v101, v115, v1
	v_add_f32_e32 v100, v105, v100
	v_exp_f32_e32 v109, v101
	v_add_f32_e32 v100, v106, v100
	v_add_f32_e32 v100, v107, v100
	v_add_f32_e32 v100, v108, v100
	v_add_f32_e32 v100, v109, v100
	v_mov_b32_e32 v101, v100
	s_nop 1
	v_permlane16_swap_b32 v101, v100
	v_cmp_neq_f32_e32 vcc, v1, v150
	s_waitcnt lgkmcnt(0)
	v_add_f32_e32 v100, v100, v101
	v_mov_b32_e32 v101, v100
	s_nop 1
	v_permlane32_swap_b32 v101, v100
	s_cbranch_vccz .LBB0_295
	v_sub_f32_e32 v110, v150, v1
	v_exp_f32_e32 v110, v110
	s_nop 0
	v_mul_f32_e32 v117, v117, v110
	v_pk_mul_f32 v[54:55], v[54:55], v[110:111] op_sel_hi:[1,0]
	v_pk_mul_f32 v[52:53], v[52:53], v[110:111] op_sel_hi:[1,0]
	v_pk_mul_f32 v[58:59], v[58:59], v[110:111] op_sel_hi:[1,0]
	v_pk_mul_f32 v[56:57], v[56:57], v[110:111] op_sel_hi:[1,0]
	v_pk_mul_f32 v[46:47], v[46:47], v[110:111] op_sel_hi:[1,0]
	v_pk_mul_f32 v[44:45], v[44:45], v[110:111] op_sel_hi:[1,0]
	v_pk_mul_f32 v[38:39], v[38:39], v[110:111] op_sel_hi:[1,0]
	v_pk_mul_f32 v[36:37], v[36:37], v[110:111] op_sel_hi:[1,0]
	v_pk_mul_f32 v[30:31], v[30:31], v[110:111] op_sel_hi:[1,0]
	v_pk_mul_f32 v[28:29], v[28:29], v[110:111] op_sel_hi:[1,0]
	v_pk_mul_f32 v[22:23], v[22:23], v[110:111] op_sel_hi:[1,0]
	v_pk_mul_f32 v[20:21], v[20:21], v[110:111] op_sel_hi:[1,0]
	v_pk_mul_f32 v[18:19], v[18:19], v[110:111] op_sel_hi:[1,0]
	v_pk_mul_f32 v[16:17], v[16:17], v[110:111] op_sel_hi:[1,0]
	v_pk_mul_f32 v[6:7], v[6:7], v[110:111] op_sel_hi:[1,0]
	v_pk_mul_f32 v[4:5], v[4:5], v[110:111] op_sel_hi:[1,0]

; __device__ __forceinline__ unsigned f2bf(float f) { return pk2(f, 0.f) & 0xffffu; }
; __device__ __forceinline__ float sum16(float v) { v += __shfl_xor(v, 1); v += __shfl_xor(v, 2); v += __shfl_xor(v, 4); v += __shfl_xor(v, 8); return v; }
; __device__ __forceinline__ void mlstm_unit(int unit, int l, const bf16_t* proj, const float* gif, const float* conv_w, const float* conv_b, bf16_t* mpart, float* dpart, int gplanes, LAS unsigned char* lds) {
;     ...
;                 const int t = 16 * mt + 4 * g + j; const float bt = bcum[t];
;                 const int sa = 16 * nt0 + c16, sb = sa + 16;
;                 const float va = (sa <= t) ? s0[j] * __expf(bt - bcum[sa] + ig[sa]) * 0.0625f : 0.f;
;                 const float vb = (sb <= t) ? s1[j] * __expf(bt - bcum[sb] + ig[sb]) * 0.0625f : 0.f;
;                 AS[t * 72 + sa] = (bf16_t)f2bf(va); AS[t * 72 + sb] = (bf16_t)f2bf(vb);
;                 rs[j] = sum16(va + vb);
;             }
;             if (c16 == 0) {
; #pragma unroll
;                 for (int j = 0; j < 4; ++j) dsum[(wid & 1) * 64 + 16 * mt + 4 * g + j] = rs[j];
.LBB0_434:
	s_or_b64 exec, exec, s[90:91]
	v_and_b32_e32 v104, 64, v217
	v_xor_b32_e32 v72, 1, v217
	v_add_u32_e32 v83, 64, v104
	v_cmp_lt_i32_e32 vcc, v72, v83
	v_xor_b32_e32 v76, 2, v217
	s_waitcnt lgkmcnt(0)
	v_xor_b32_e32 v80, 4, v217
	v_cndmask_b32_e32 v72, v217, v72, vcc
	v_cmp_lt_i32_e32 vcc, v76, v83
	v_xor_b32_e32 v87, 8, v217
	v_lshlrev_b32_e32 v72, 2, v72
	v_cndmask_b32_e32 v76, v217, v76, vcc
	v_cmp_lt_i32_e32 vcc, v80, v83
	v_lshlrev_b32_e32 v76, 2, v76
	ds_read_b32 v88, v82 offset:4
	v_cndmask_b32_e32 v80, v217, v80, vcc
	v_cmp_lt_i32_e32 vcc, v87, v83
	v_lshlrev_b32_e32 v80, 2, v80
	s_nop 0
	v_cndmask_b32_e32 v83, v217, v87, vcc
	v_cvt_pk_bf16_f32 v87, v84, s0
	v_add_f32_e32 v84, v84, v85
	ds_write_b16 v123, v87
	v_cvt_pk_bf16_f32 v87, v85, s0
	s_nop 1
	v_mov_b32_dpp v85, v84 quad_perm:[1,0,3,2] row_mask:0xf bank_mask:0xf
	v_lshlrev_b32_e32 v83, 2, v83
	ds_write_b16 v123, v87 offset:32
	s_waitcnt lgkmcnt(1)
	v_add_f32_e32 v84, v84, v85
	s_nop 1
	v_mov_b32_dpp v85, v84 quad_perm:[2,3,0,1] row_mask:0xf bank_mask:0xf
	s_waitcnt lgkmcnt(0)
	v_add_f32_e32 v84, v84, v85
	s_nop 1
	v_mov_b32_dpp v85, v84 row_half_mirror row_mask:0xf bank_mask:0xf
	s_waitcnt lgkmcnt(0)
	v_add_f32_e32 v84, v84, v85
	s_nop 1
	v_mov_b32_dpp v85, v84 row_mirror row_mask:0xf bank_mask:0xf
	s_and_saveexec_b64 s[90:91], s[50:51]
	s_cbranch_execz .LBB0_436
	ds_read2st64_b32 v[86:87], v81 offset1:1
	s_waitcnt lgkmcnt(0)
	v_sub_f32_e32 v86, v88, v86
	v_add_f32_e32 v86, v86, v87
	v_mul_f32_e32 v86, 0x3fb8aa3b, v86
	v_exp_f32_e32 v86, v86
	s_nop 0
	v_mul_f32_e32 v77, v77, v86
	v_mul_f32_e32 v86, 0x3d800000, v77

; __device__ __forceinline__ unsigned f2bf(float f) { return pk2(f, 0.f) & 0xffffu; }
; __device__ __forceinline__ float sum16(float v) { v += __shfl_xor(v, 1); v += __shfl_xor(v, 2); v += __shfl_xor(v, 4); v += __shfl_xor(v, 8); return v; }
; __device__ __forceinline__ void mlstm_unit(int unit, int l, const bf16_t* proj, const float* gif, const float* conv_w, const float* conv_b, bf16_t* mpart, float* dpart, int gplanes, LAS unsigned char* lds) {
;     ...
;                 const int t = 16 * mt + 4 * g + j; const float bt = bcum[t];
;                 const int sa = 16 * nt0 + c16, sb = sa + 16;
;                 const float va = (sa <= t) ? s0[j] * __expf(bt - bcum[sa] + ig[sa]) * 0.0625f : 0.f;
;                 const float vb = (sb <= t) ? s1[j] * __expf(bt - bcum[sb] + ig[sb]) * 0.0625f : 0.f;
;                 AS[t * 72 + sa] = (bf16_t)f2bf(va); AS[t * 72 + sb] = (bf16_t)f2bf(vb);
;                 rs[j] = sum16(va + vb);
.LBB0_438:
	s_or_b64 exec, exec, s[90:91]
	v_cvt_pk_bf16_f32 v73, v86, s0
	ds_write_b16 v163, v73
	v_cvt_pk_bf16_f32 v73, v77, s0
	ds_write_b16 v163, v73 offset:32
	v_add_f32_e32 v73, v86, v77
	s_nop 1
	v_mov_b32_dpp v77, v73 quad_perm:[1,0,3,2] row_mask:0xf bank_mask:0xf
	ds_read_b32 v86, v82 offset:8
	s_waitcnt lgkmcnt(1)
	v_add_f32_e32 v73, v73, v77
	s_nop 1
	v_mov_b32_dpp v77, v73 quad_perm:[2,3,0,1] row_mask:0xf bank_mask:0xf
	s_waitcnt lgkmcnt(0)
	v_add_f32_e32 v73, v73, v77
	s_nop 1
	v_mov_b32_dpp v77, v73 row_half_mirror row_mask:0xf bank_mask:0xf
	s_waitcnt lgkmcnt(0)
	v_add_f32_e32 v73, v73, v77
	s_nop 1
	v_mov_b32_dpp v77, v73 row_mirror row_mask:0xf bank_mask:0xf
	s_and_saveexec_b64 s[90:91], s[54:55]
	s_cbranch_execz .LBB0_440
	ds_read2st64_b32 v[88:89], v81 offset1:1
	s_waitcnt lgkmcnt(0)
	v_sub_f32_e32 v87, v86, v88
	v_add_f32_e32 v87, v87, v89
	v_mul_f32_e32 v87, 0x3fb8aa3b, v87
	v_exp_f32_e32 v87, v87
	s_nop 0
	v_mul_f32_e32 v78, v78, v87
	v_mul_f32_e32 v87, 0x3d800000, v78

; __device__ __forceinline__ unsigned f2bf(float f) { return pk2(f, 0.f) & 0xffffu; }
; __device__ __forceinline__ float sum16(float v) { v += __shfl_xor(v, 1); v += __shfl_xor(v, 2); v += __shfl_xor(v, 4); v += __shfl_xor(v, 8); return v; }
; __device__ __forceinline__ void mlstm_unit(int unit, int l, const bf16_t* proj, const float* gif, const float* conv_w, const float* conv_b, bf16_t* mpart, float* dpart, int gplanes, LAS unsigned char* lds) {
;     ...
;                 const int t = 16 * mt + 4 * g + j; const float bt = bcum[t];
;                 const int sa = 16 * nt0 + c16, sb = sa + 16;
;                 const float va = (sa <= t) ? s0[j] * __expf(bt - bcum[sa] + ig[sa]) * 0.0625f : 0.f;
;                 const float vb = (sb <= t) ? s1[j] * __expf(bt - bcum[sb] + ig[sb]) * 0.0625f : 0.f;
;                 AS[t * 72 + sa] = (bf16_t)f2bf(va); AS[t * 72 + sb] = (bf16_t)f2bf(vb);
;                 rs[j] = sum16(va + vb);
.LBB0_442:
	s_or_b64 exec, exec, s[90:91]
	v_cvt_pk_bf16_f32 v74, v87, s0
	ds_write_b16 v164, v74
	v_cvt_pk_bf16_f32 v74, v88, s0
	ds_write_b16 v164, v74 offset:32
	v_add_f32_e32 v74, v87, v88
	s_nop 1
	v_mov_b32_dpp v86, v74 quad_perm:[1,0,3,2] row_mask:0xf bank_mask:0xf
	ds_read_b32 v82, v82 offset:12
	s_waitcnt lgkmcnt(1)
	v_add_f32_e32 v74, v74, v86
	s_nop 1
	v_mov_b32_dpp v86, v74 quad_perm:[2,3,0,1] row_mask:0xf bank_mask:0xf
	s_waitcnt lgkmcnt(0)
	v_add_f32_e32 v74, v74, v86
	s_nop 1
	v_mov_b32_dpp v86, v74 row_half_mirror row_mask:0xf bank_mask:0xf
	s_waitcnt lgkmcnt(0)
	v_add_f32_e32 v74, v74, v86
	s_nop 1
	v_mov_b32_dpp v86, v74 row_mirror row_mask:0xf bank_mask:0xf
	s_and_saveexec_b64 s[90:91], s[58:59]
	s_cbranch_execz .LBB0_444
	ds_read2st64_b32 v[88:89], v81 offset1:1
	s_waitcnt lgkmcnt(0)
	v_sub_f32_e32 v78, v82, v88
	v_add_f32_e32 v78, v78, v89
	v_mul_f32_e32 v78, 0x3fb8aa3b, v78
	v_exp_f32_e32 v78, v78
	s_nop 0
	v_mul_f32_e32 v78, v79, v78
	v_mul_f32_e32 v78, 0x3d800000, v78

; #define LAS __attribute__((address_space(3)))
; __device__ __forceinline__ unsigned f2bf(float f) { return pk2(f, 0.f) & 0xffffu; }
; __device__ __forceinline__ float sum16(float v) { v += __shfl_xor(v, 1); v += __shfl_xor(v, 2); v += __shfl_xor(v, 4); v += __shfl_xor(v, 8); return v; }
; __device__ __forceinline__ void mlstm_unit(int unit, int l, const bf16_t* proj, const float* gif, const float* conv_w, const float* conv_b, bf16_t* mpart, float* dpart, int gplanes, LAS unsigned char* lds) {
;     ...
;                 const float va = (sa <= t) ? s0[j] * __expf(bt - bcum[sa] + ig[sa]) * 0.0625f : 0.f;
;                 const float vb = (sb <= t) ? s1[j] * __expf(bt - bcum[sb] + ig[sb]) * 0.0625f : 0.f;
;                 AS[t * 72 + sa] = (bf16_t)f2bf(va); AS[t * 72 + sb] = (bf16_t)f2bf(vb);
;                 rs[j] = sum16(va + vb);
;             }
;             if (c16 == 0) {
; #pragma unroll
;                 for (int j = 0; j < 4; ++j) dsum[(wid & 1) * 64 + 16 * mt + 4 * g + j] = rs[j];
;             }
;             const int t = tid >> 3, part = tid & 7; float p = 0.f;
;             { const u32x4 qv = *(const LAS u32x4*)(Q + t * 72 + part * 8); float qf[8]; unpack8(qv, qf);
; #pragma unroll
;               for (int j = 0; j < 8; ++j) p += qf[j] * nvec[part * 8 + j]; }
;             p += __shfl_xor(p, 1); p += __shfl_xor(p, 2); p += __shfl_xor(p, 4);
;             if (part == 0) qn[t] = p;
.LBB0_446:
	s_or_b64 exec, exec, s[90:91]
	v_cvt_pk_bf16_f32 v75, v78, s0
	ds_write_b16 v165, v75
	v_cvt_pk_bf16_f32 v75, v79, s0
	ds_write_b16 v165, v75 offset:32
	v_add_f32_e32 v75, v78, v79
	s_nop 1
	v_mov_b32_dpp v78, v75 quad_perm:[1,0,3,2] row_mask:0xf bank_mask:0xf
	s_waitcnt lgkmcnt(0)
	v_add_f32_e32 v75, v75, v78
	s_nop 1
	v_mov_b32_dpp v78, v75 quad_perm:[2,3,0,1] row_mask:0xf bank_mask:0xf
	s_waitcnt lgkmcnt(0)
	v_add_f32_e32 v75, v75, v78
	s_nop 1
	v_mov_b32_dpp v78, v75 row_half_mirror row_mask:0xf bank_mask:0xf
	s_waitcnt lgkmcnt(0)
	v_add_f32_e32 v75, v75, v78
	s_nop 1
	v_mov_b32_dpp v78, v75 row_mirror row_mask:0xf bank_mask:0xf
	s_and_saveexec_b64 s[90:91], s[42:43]
	s_cbranch_execz .LBB0_448
	v_add_f32_e32 v88, v74, v86
	v_add_f32_e32 v87, v73, v77
	v_add_f32_e32 v86, v84, v85
	s_waitcnt lgkmcnt(0)
	v_add_f32_e32 v89, v75, v78
	ds_write_b128 v173, v[86:89]
.LBB0_448:
	s_or_b64 exec, exec, s[90:91]
	ds_read_b128 v[82:85], v174
	ds_read_b128 v[86:89], v156
	s_waitcnt lgkmcnt(1)
	v_lshlrev_b32_e32 v73, 16, v82
	v_and_b32_e32 v74, 0xffff0000, v82
	v_lshlrev_b32_e32 v75, 16, v83
	v_and_b32_e32 v77, 0xffff0000, v83
	v_lshlrev_b32_e32 v78, 16, v84
	v_and_b32_e32 v79, 0xffff0000, v84
	v_lshlrev_b32_e32 v81, 16, v85
	v_and_b32_e32 v90, 0xffff0000, v85
	ds_read_b128 v[82:85], v156 offset:16
	s_waitcnt lgkmcnt(1)
	v_fma_f32 v73, v86, v73, 0
	v_fmac_f32_e32 v73, v87, v74
	v_fmac_f32_e32 v73, v88, v75
	v_fmac_f32_e32 v73, v89, v77
	s_waitcnt lgkmcnt(0)
	v_fmac_f32_e32 v73, v82, v78
	v_fmac_f32_e32 v73, v83, v79
	v_fmac_f32_e32 v73, v84, v81
	v_fmac_f32_e32 v73, v85, v90
	s_nop 1
	v_mov_b32_dpp v72, v73 quad_perm:[1,0,3,2] row_mask:0xf bank_mask:0xf
	s_waitcnt lgkmcnt(0)
	v_add_f32_e32 v72, v73, v72
	s_nop 1
	v_mov_b32_dpp v73, v72 quad_perm:[2,3,0,1] row_mask:0xf bank_mask:0xf
	s_waitcnt lgkmcnt(0)
	v_add_f32_e32 v72, v72, v73
	s_nop 1
	v_mov_b32_dpp v73, v72 row_half_mirror row_mask:0xf bank_mask:0xf
	s_and_saveexec_b64 s[90:91], s[44:45]
	s_cbranch_execz .LBB0_450
	s_waitcnt lgkmcnt(0)
	v_add_f32_e32 v72, v72, v73
	ds_write_b32 v157, v72

; __device__ __forceinline__ unsigned f2bf(float f) { return pk2(f, 0.f) & 0xffffu; }
; #define MFMA16(a, b, c) __builtin_amdgcn_mfma_f32_16x16x32_bf16((a), (b), (c), 0, 0, 0)
; __device__ __forceinline__ void mlstm_unit(int unit, int l, const bf16_t* proj, const float* gif, const float* conv_w, const float* conv_b, bf16_t* mpart, float* dpart, int gplanes, LAS unsigned char* lds) {
;     ...
;             const float dec = __expf(Gc);
; #pragma unroll
;             for (int a = 0; a < 2; ++a)
; #pragma unroll
;                 for (int n = 0; n < 4; ++n) ct[a][n] = ct[a][n] * dec;
; #pragma unroll
;             for (int ks = 0; ks < 2; ++ks) {
;                 const bf16x8 a0 = trfrag(VW, 264, 32 * ks, 16 * (2 * wid), lane), a1 = trfrag(VW, 264, 32 * ks, 16 * (2 * wid + 1), lane);
; #pragma unroll
;                 for (int n = 0; n < 4; ++n) { const bf16x8 bk = trfrag(KK, 72, 32 * ks, 16 * n, lane); ct[0][n] = MFMA16(a0, bk, ct[0][n]); ct[1][n] = MFMA16(a1, bk, ct[1][n]); }
;             }
; #pragma unroll
;             for (int a = 0; a < 2; ++a)
; #pragma unroll
;                 for (int n = 0; n < 4; ++n)
; #pragma unroll
;                     for (int j = 0; j < 4; ++j) ST[(16 * (2 * wid + a) + 4 * g + j) * 72 + 16 * n + c16] = (bf16_t)f2bf(ct[a][n][j]);
;             {
;                 float sn = 0.f;
; #pragma unroll
;                 for (int i = 0; i < 8; ++i) sn += wsc[wid * 8 + i] * bf2f(KK[(wid * 8 + i) * 72 + lane]);
;                 npart[wid * 64 + lane] = sn;
.LBB0_452:
	s_or_b64 exec, exec, s[90:91]
	v_mul_f32_e32 v1, 0x3fb8aa3b, v1
	v_exp_f32_e32 v76, v1
	s_lshl_b32 s8, s4, 2
	s_add_i32 s7, s7, s8
	s_or_b64 s[8:9], s[80:81], s[76:77]
	v_pk_mul_f32 v[74:75], v[42:43], v[76:77] op_sel_hi:[1,0]
	v_pk_mul_f32 v[72:73], v[40:41], v[76:77] op_sel_hi:[1,0]
	v_pk_mul_f32 v[50:51], v[50:51], v[76:77] op_sel_hi:[1,0]
	v_pk_mul_f32 v[48:49], v[48:49], v[76:77] op_sel_hi:[1,0]
	v_pk_mul_f32 v[58:59], v[58:59], v[76:77] op_sel_hi:[1,0]
	v_pk_mul_f32 v[56:57], v[56:57], v[76:77] op_sel_hi:[1,0]
	v_pk_mul_f32 v[42:43], v[66:67], v[76:77] op_sel_hi:[1,0]
	v_pk_mul_f32 v[40:41], v[64:65], v[76:77] op_sel_hi:[1,0]
	v_pk_mul_f32 v[66:67], v[46:47], v[76:77] op_sel_hi:[1,0]
	v_pk_mul_f32 v[64:65], v[44:45], v[76:77] op_sel_hi:[1,0]
	v_pk_mul_f32 v[54:55], v[54:55], v[76:77] op_sel_hi:[1,0]
	v_pk_mul_f32 v[52:53], v[52:53], v[76:77] op_sel_hi:[1,0]
	v_pk_mul_f32 v[62:63], v[62:63], v[76:77] op_sel_hi:[1,0]
	v_pk_mul_f32 v[60:61], v[60:61], v[76:77] op_sel_hi:[1,0]
	v_pk_mul_f32 v[46:47], v[70:71], v[76:77] op_sel_hi:[1,0]
	v_pk_mul_f32 v[44:45], v[68:69], v[76:77] op_sel_hi:[1,0]
	ds_read_b64_tr_b16 v[70:71], v166 offset:54336
	ds_read_b64_tr_b16 v[68:69], v166 offset:52224
	ds_read_b64_tr_b16 v[76:77], v166 offset:52256
	ds_read_b64_tr_b16 v[78:79], v166 offset:54368
	ds_read_b64_tr_b16 v[82:83], v175 offset:9792
	ds_read_b64_tr_b16 v[80:81], v175 offset:9216
	ds_read_b64_tr_b16 v[84:85], v175 offset:9248
	s_waitcnt lgkmcnt(1)
	v_mfma_f32_16x16x32_bf16 v[72:75], v[68:71], v[80:83], v[72:75]
	ds_read_b64_tr_b16 v[86:87], v175 offset:9824
	s_add_i32 s36, s36, 1
	s_and_b64 vcc, exec, s[8:9]
	v_mfma_f32_16x16x32_bf16 v[64:67], v[76:79], v[80:83], v[64:67]
	ds_read_b64_tr_b16 v[80:81], v175 offset:9280
	ds_read_b64_tr_b16 v[82:83], v175 offset:9856
	s_waitcnt lgkmcnt(0)
	v_mfma_f32_16x16x32_bf16 v[56:59], v[68:71], v[80:83], v[56:59]
	v_mfma_f32_16x16x32_bf16 v[60:63], v[76:79], v[80:83], v[60:63]
	ds_read_b64_tr_b16 v[80:81], v175 offset:9312
	ds_read_b64_tr_b16 v[82:83], v175 offset:9888
	v_mfma_f32_16x16x32_bf16 v[48:51], v[68:71], v[84:87], v[48:51]
	v_mfma_f32_16x16x32_bf16 v[52:55], v[76:79], v[84:87], v[52:55]
	s_waitcnt lgkmcnt(0)
	v_mfma_f32_16x16x32_bf16 v[68:71], v[68:71], v[80:83], v[40:43]
	v_mfma_f32_16x16x32_bf16 v[76:79], v[76:79], v[80:83], v[44:47]
	ds_read_b64_tr_b16 v[82:83], v172 offset:54336
	ds_read_b64_tr_b16 v[80:81], v172 offset:52224
	ds_read_b64_tr_b16 v[84:85], v172 offset:52256
	ds_read_b64_tr_b16 v[86:87], v172 offset:54368
	ds_read_b64_tr_b16 v[44:45], v175 offset:13824
	ds_read_b64_tr_b16 v[46:47], v175 offset:14400
	s_waitcnt lgkmcnt(0)
	v_mfma_f32_16x16x32_bf16 v[40:43], v[80:83], v[44:47], v[72:75]
	v_mfma_f32_16x16x32_bf16 v[44:47], v[84:87], v[44:47], v[64:67]
	s_nop 2
	ds_read_b64_tr_b16 v[64:65], v175 offset:13856
	ds_read_b64_tr_b16 v[66:67], v175 offset:14432
	s_nop 1
	v_cvt_pk_bf16_f32 v1, v40, s0
	s_waitcnt lgkmcnt(0)
	v_mfma_f32_16x16x32_bf16 v[48:51], v[80:83], v[64:67], v[48:51]
	v_mfma_f32_16x16x32_bf16 v[52:55], v[84:87], v[64:67], v[52:55]
	ds_read_b64_tr_b16 v[64:65], v175 offset:13888
	ds_read_b64_tr_b16 v[66:67], v175 offset:14464
	ds_read_b64_tr_b16 v[72:73], v175 offset:13920
	ds_read_b64_tr_b16 v[74:75], v175 offset:14496
	ds_write_b16 v176, v1
	v_cvt_pk_bf16_f32 v1, v41, s0
	ds_write_b16 v176, v1 offset:144
	v_cvt_pk_bf16_f32 v1, v42, s0
	ds_write_b16 v176, v1 offset:288
	v_cvt_pk_bf16_f32 v1, v43, s0
	s_waitcnt lgkmcnt(5)
	v_mfma_f32_16x16x32_bf16 v[56:59], v[80:83], v[64:67], v[56:59]
	ds_write_b16 v176, v1 offset:432
	v_cvt_pk_bf16_f32 v1, v48, s0
	ds_write_b16 v176, v1 offset:32
	v_cvt_pk_bf16_f32 v1, v49, s0
	ds_write_b16 v176, v1 offset:176
	v_cvt_pk_bf16_f32 v1, v50, s0
	ds_write_b16 v176, v1 offset:320
	v_cvt_pk_bf16_f32 v1, v51, s0
	v_mfma_f32_16x16x32_bf16 v[60:63], v[84:87], v[64:67], v[60:63]
	ds_write_b16 v176, v1 offset:464
	v_cvt_pk_bf16_f32 v1, v56, s0
	ds_write_b16 v176, v1 offset:64
	s_waitcnt lgkmcnt(9)
	v_mfma_f32_16x16x32_bf16 v[64:67], v[80:83], v[72:75], v[68:71]
	v_cvt_pk_bf16_f32 v1, v57, s0
	ds_write_b16 v176, v1 offset:208
	v_cvt_pk_bf16_f32 v1, v58, s0
	ds_write_b16 v176, v1 offset:352
	v_cvt_pk_bf16_f32 v1, v59, s0
	ds_write_b16 v176, v1 offset:496
	s_nop 1
	v_cvt_pk_bf16_f32 v1, v64, s0
	ds_write_b16 v176, v1 offset:96
	v_cvt_pk_bf16_f32 v1, v65, s0
	ds_write_b16 v176, v1 offset:240
	v_cvt_pk_bf16_f32 v1, v66, s0
	ds_write_b16 v176, v1 offset:384
	v_cvt_pk_bf16_f32 v1, v67, s0
	ds_write_b16 v176, v1 offset:528
	v_cvt_pk_bf16_f32 v1, v44, s0
	ds_write_b16 v176, v1 offset:2304
	v_cvt_pk_bf16_f32 v1, v45, s0
	ds_write_b16 v176, v1 offset:2448
	v_cvt_pk_bf16_f32 v1, v46, s0
	ds_write_b16 v176, v1 offset:2592
	v_cvt_pk_bf16_f32 v1, v47, s0
	ds_write_b16 v176, v1 offset:2736
	v_cvt_pk_bf16_f32 v1, v52, s0
	ds_write_b16 v176, v1 offset:2336
	v_cvt_pk_bf16_f32 v1, v53, s0
	ds_write_b16 v176, v1 offset:2480
	v_cvt_pk_bf16_f32 v1, v54, s0
	ds_write_b16 v176, v1 offset:2624
	v_cvt_pk_bf16_f32 v1, v55, s0
	v_mfma_f32_16x16x32_bf16 v[68:71], v[84:87], v[72:75], v[76:79]
	ds_write_b16 v176, v1 offset:2768
	v_cvt_pk_bf16_f32 v1, v60, s0
	ds_write_b16 v176, v1 offset:2368
	v_cvt_pk_bf16_f32 v1, v61, s0
	ds_write_b16 v176, v1 offset:2512
	v_cvt_pk_bf16_f32 v1, v62, s0
	ds_write_b16 v176, v1 offset:2656
	v_cvt_pk_bf16_f32 v1, v63, s0
	ds_write_b16 v176, v1 offset:2800
	v_cvt_pk_bf16_f32 v1, v68, s0
	ds_write_b16 v176, v1 offset:2400
	v_cvt_pk_bf16_f32 v1, v69, s0
	ds_write_b16 v176, v1 offset:2544
	v_cvt_pk_bf16_f32 v1, v70, s0
	ds_write_b16 v176, v1 offset:2688
	v_cvt_pk_bf16_f32 v1, v71, s0
	ds_write_b16 v176, v1 offset:2832
	v_mov_b32_e32 v1, s7
	ds_read_b128 v[72:75], v1 offset:512
	ds_read_b128 v[76:79], v1 offset:528
	v_add_u32_e32 v1, s5, v162
	ds_read_u16 v1, v1 offset:9216
	v_add_u32_e32 v80, s6, v162
	ds_read_u16 v81, v80 offset:9216
	ds_read_u16 v82, v80 offset:9360
	ds_read_u16 v83, v80 offset:9504
	ds_read_u16 v84, v80 offset:9648
	ds_read_u16 v85, v80 offset:9792
	ds_read_u16 v86, v80 offset:9936
	ds_read_u16 v87, v80 offset:10080
	s_waitcnt lgkmcnt(0)
	v_lshlrev_b32_e32 v1, 16, v1
	v_fma_f32 v1, v72, v1, 0
	v_lshlrev_b32_e32 v81, 16, v81
	v_fmac_f32_e32 v1, v73, v81
	v_lshlrev_b32_e32 v82, 16, v82
	v_fmac_f32_e32 v1, v74, v82
	v_lshlrev_b32_e32 v83, 16, v83
	v_fmac_f32_e32 v1, v75, v83
	v_lshlrev_b32_e32 v84, 16, v84
	v_fmac_f32_e32 v1, v76, v84
	v_lshlrev_b32_e32 v85, 16, v85
	v_fmac_f32_e32 v1, v77, v85
	v_lshlrev_b32_e32 v86, 16, v86
	v_fmac_f32_e32 v1, v78, v86
	v_lshlrev_b32_e32 v87, 16, v87
	v_fmac_f32_e32 v1, v79, v87
	ds_write_b32 v177, v1
	s_cbranch_vccz .LBB0_421
	s_waitcnt vmcnt(9)
	v_mov_b32_e32 v72, v130
	s_waitcnt vmcnt(8)
	v_mov_b32_e32 v73, v129
	s_branch .LBB0_422
